# phase_post K-gain loads batched; diff-attention far-tile bias read once per item; mixer queue reordered so weight-conversion items precede the short memory-attention items
# speedup vs baseline: 1.1994x; 1.0109x over previous
; __device__ __forceinline__ void phase_mixer(const Params& p, unsigned char* sm, const int TIDX, const int BIDX, const int rep) {
;     ...
;     for (;;) {
;         __syncthreads();
;         if (TIDX == 0) *sitem = (int)atomicAdd(ctr, 1u);
;         __syncthreads();
;         int it = __builtin_amdgcn_readfirstlane(*sitem);
;         int tl = TIDX; asm volatile("" : "+v"(tl));
;         if (it >= 1760 + 258) break;
;         if (it >= 1760) { if (rep == 0) { int tl2 = TIDX; asm volatile("" : "+v"(tl2)); conv_item(p, sm, 1, it - 1760, tl2); } continue; }
;         int kind, h, a0, a1, a2, a3, a4, a5; const float* sin = nullptr; float* sout = nullptr;
;         if (it < 32) { const int b = it >> 2; h = it & 3; kind = 0; a0 = (b * 32) * 4 + h; a1 = 32; a2 = b * 2048; a3 = 64; a4 = 0; a5 = 0; sout = p.out + O_GSP + (size_t)(b * 4 + h) * 32768; }
;         else if (it < 544 || (it >= 608 && it < 1120)) { it -= (it < 544 ? 32 : 96); const int qc = 31 - (it >> 5), bh = it & 31, b = bh >> 2; h = bh & 3; kind = 1;
;             a0 = b * 2048 + qc * 64; a1 = 64; a2 = (b * 4 + h) * 32; a3 = qc + 1; a4 = (qc + 1) * 64; a5 = qc * 64; }
;         else if (it < 608) { it -= 544; const int sb = it >> 2; h = it & 3; kind = 1; a0 = TP + sb * 32; a1 = 32; a2 = 1024 + (sb * 4 + h) * 17; a3 = 17; a4 = 1056; a5 = 1024; }
;         else if (it < 1184) { it -= 1120; const int sb = it >> 2; h = it & 3; kind = 0; a0 = (256 + sb) * 4 + h; a1 = 1; a2 = TP + sb * 32; a3 = 32; a4 = 0; a5 = 0;
;             sin = p.in[5] + (size_t)(sb * 4 + h) * 32768; sout = p.out + O_GSS + (size_t)(sb * 4 + h) * 32768; }
;         else if (it < 1696) { it -= 1184; const int qb = it & 15, bh = it >> 4, b = bh >> 2; h = bh & 3; kind = 2; a0 = b * 2048 + qb * 128; a1 = 128; a2 = 2112 + (b * 4 + h) * 4; a3 = 4; a4 = 256; a5 = 0; }
;         else { it -= 1696; const int sb = it >> 2; h = it & 3; kind = 2; a0 = TP + sb * 32; a1 = 32; a2 = 2240 + (sb * 4 + h) * 4; a3 = 4; a4 = 256; a5 = 0; }
.LBB0_46:
	s_or_b64 exec, exec, s[6:7]
	v_mov_b32_e32 v0, s83
	s_waitcnt lgkmcnt(0)
	s_barrier
	ds_read_b32 v0, v0
	v_mov_b32_e32 v116, v199
	s_mov_b64 s[6:7], -1
	s_waitcnt lgkmcnt(0)
	v_readfirstlane_b32 s44, v0
	s_cmpk_gt_i32 s44, 0x7e1
	s_cbranch_scc1 .LBB0_41
	s_cmpk_lt_u32 s44, 0x4a0
	s_cbranch_scc1 .Lq_keep
	s_cmpk_lt_u32 s44, 0x5a2
	s_cbranch_scc1 .Lq_conv
	s_sub_i32 s44, s44, 258
	s_branch .Lq_keep
.Lq_conv:
	s_add_i32 s44, s44, 576
.Lq_keep:
	s_cmpk_lt_i32 s44, 0x6e0
	s_cbranch_scc0 .LBB0_178
	s_cmp_gt_i32 s44, 31
	s_mov_b64 s[12:13], -1
	s_cbranch_scc0 .LBB0_60
	s_cmpk_lt_u32 s44, 0x220
	s_cselect_b64 s[12:13], -1, 0
	s_and_b64 vcc, exec, s[12:13]
	s_cbranch_vccnz .LBB0_63
	s_add_i32 s6, s44, 0xfffffda0
	s_cmpk_gt_u32 s6, 0x1ff
	s_mov_b64 s[12:13], -1
	s_cbranch_scc0 .LBB0_67
	s_cmpk_gt_u32 s44, 0x25f
	s_mov_b64 s[10:11], -1
	s_cbranch_scc0 .LBB0_65
	s_cmpk_gt_u32 s44, 0x49f
	s_mov_b64 s[6:7], -1
	s_cbranch_scc0 .LBB0_58
	s_cmpk_gt_u32 s44, 0x69f
	s_cbranch_scc0 .LBB0_55
	s_add_i32 s6, s44, 0xfffff960
	s_lshl_b32 s7, s6, 3
	s_and_b32 s7, s7, 0x7fffffe0
	s_lshl_b32 s6, s6, 2
	s_and_b32 s16, s44, 3
	s_add_i32 s96, s7, 0x4000
	s_add_i32 s98, s6, 0x8c0
	s_mov_b64 s[6:7], 0

; #define BAR_LDS() do { asm volatile("s_waitcnt lgkmcnt(0)" ::: "memory"); __builtin_amdgcn_s_barrier(); asm volatile("" ::: "memory"); } while (0)
; #define AT_LOAD(t) do { _Pragma("unroll") for (int k_ = 0; k_ < 2; ++k_) { const int id_ = tid + 512 * k_; pkk[k_] = *(const u32x4*)(kvg + (size_t)(t) * 32768 + id_ * 16); pvv[k_] = *(const u32x4*)(kvg + (size_t)(t) * 32768 + 16384 + id_ * 16); } } while (0)
; #define AT_STORE(buf) do { unsigned char* b_ = sm + (buf) * 35840; _Pragma("unroll") for (int k_ = 0; k_ < 2; ++k_) { const int id_ = tid + 512 * k_; \
;         *(u32x4*)(b_ + (id_ >> 4) * 272 + (id_ & 15) * 16) = pkk[k_]; *(u32x4*)(b_ + 17408 + (id_ >> 3) * 144 + (id_ & 7) * 16) = pvv[k_]; } } while (0)
; template <int MODE>
; __device__ __forceinline__ void attn_item(const Params& p, unsigned char* sm, int h, int tok0, int nrows, int kvt0, int ntiles, int nkeys, int qpos0, const int TIDX) {
;     ...
;     const unsigned char* kvg = p.ws + WS_KV + (size_t)kvt0 * 32768;
;     u32x4 pkk[2], pvv[2];
;     ...
;     AT_LOAD(0); AT_STORE(0);
;     BAR_LDS();
;     const float SC = (MODE == 0 ? 0.125f : 0.08838834764831845f) * LOG2E;
;     float m_run = -1e30f, l_run = 0.f;
;     f32x4 O[8];
; #pragma unroll
;     for (int cb = 0; cb < 8; ++cb) O[cb] = (f32x4){0.f, 0.f, 0.f, 0.f};
;     const int qpos = qpos0 + qrow;
.LBB0_93:
	s_or_b64 exec, exec, s[10:11]
	s_ashr_i32 s99, s98, 31
	s_lshl_b32 s12, s20, 6
	s_lshl_b32 s18, s16, 7
	s_lshl_b64 s[10:11], s[98:99], 15
	v_readlane_b32 s13, v255, 39
	s_add_u32 s14, s13, s10
	v_readlane_b32 s13, v255, 40
	v_lshlrev_b32_e32 v76, 4, v116
	s_addc_u32 s15, s13, s11
	v_ashrrev_i32_e32 v77, 31, v76
	v_lshl_add_u64 v[4:5], s[14:15], 0, v[76:77]
	s_add_u32 s22, s14, 0x4000
	global_load_dwordx4 v[42:45], v[4:5], off
	s_addc_u32 s23, s15, 0
	v_lshl_add_u64 v[4:5], s[22:23], 0, v[76:77]
	global_load_dwordx4 v[46:49], v[4:5], off
	v_add_u32_e32 v78, 0x2000, v76
	v_ashrrev_i32_e32 v79, 31, v78
	v_lshl_add_u64 v[4:5], s[14:15], 0, v[78:79]
	global_load_dwordx4 v[50:53], v[4:5], off
	v_lshl_add_u64 v[4:5], s[22:23], 0, v[78:79]
	global_load_dwordx4 v[54:57], v[4:5], off
	v_and_b32_e32 v98, 0xf0, v76
	v_lshrrev_b32_e32 v5, 4, v116
	v_add_u32_e32 v3, 0, v98
	v_mul_lo_u32 v100, v5, s74
	v_add_u32_e32 v5, v3, v100
	v_and_b32_e32 v99, 0x70, v76
	s_movk_i32 s13, 0x90
	v_add_u32_e32 v4, 0, v99
	v_bfe_u32 v96, v116, 4, 2
	v_and_b32_e32 v97, 63, v116
	v_and_b32_e32 v2, 15, v116
	v_lshlrev_b32_e32 v74, 3, v96
	s_cmp_lt_i32 s36, 1
	s_waitcnt vmcnt(0)
	ds_write_b128 v5, v[42:45]
	v_lshrrev_b32_e32 v5, 3, v116
	v_mul_lo_u32 v101, v5, s13
	v_add_u32_e32 v5, v4, v101
	s_waitcnt vmcnt(2)
	ds_write_b128 v5, v[46:49] offset:17408
	v_add_u32_e32 v5, 0x200, v116
	v_lshrrev_b32_e32 v6, 4, v5
	v_mul_lo_u32 v102, v6, s74
	v_add_u32_e32 v3, v3, v102
	s_waitcnt vmcnt(1)
	ds_write_b128 v3, v[50:53]
	v_lshrrev_b32_e32 v3, 3, v5
	v_mul_lo_u32 v103, v3, s13
	v_add_u32_e32 v3, v4, v103
	s_waitcnt vmcnt(0)
	ds_write_b128 v3, v[54:57] offset:17408
	s_waitcnt lgkmcnt(0)
	s_barrier
	s_cbranch_scc1 .LBB0_105
	s_load_dwordx16 s[48:63], s[68:69], 0xc0
	v_or_b32_e32 v3, s12, v74
	v_lshlrev_b32_e32 v106, 1, v3
	v_mov_b32_e32 v3, 0x1100
	v_add_u32_e32 v105, s19, v75
	v_mad_u32_u24 v108, v2, s74, v3
	v_mov_b32_e32 v3, 0x2200
	s_sub_i32 s19, 0, s19
	v_lshlrev_b32_e32 v104, 2, v96
	v_mad_u32_u24 v109, v2, s74, v3
	v_mov_b32_e32 v3, 0x3300
	s_waitcnt lgkmcnt(0)
	s_add_u32 s10, s62, s10
	v_mov_b32_e32 v113, 0
	v_mul_u32_u24_e32 v107, 0x110, v2
	v_mad_u32_u24 v110, v2, s74, v3
	v_mul_u32_u24_e32 v111, 0x90, v2
	s_mov_b32 s21, s17
	v_sub_u32_e32 v112, v104, v105
	s_mov_b32 s14, 0
	s_addc_u32 s11, s63, s11
	v_mov_b32_e32 v114, 0xf149f2ca
	s_mov_b32 s22, 64
	v_mov_b32_e32 v2, 0
	v_mov_b32_e32 v3, v113
	v_mov_b32_e32 v4, v113
	v_mov_b32_e32 v5, v113
	v_mov_b32_e32 v10, 0
	v_mov_b32_e32 v11, v113
	v_mov_b32_e32 v12, v113
	v_mov_b32_e32 v13, v113
	v_mov_b32_e32 v6, 0
	v_mov_b32_e32 v7, v113
	v_mov_b32_e32 v8, v113
	v_mov_b32_e32 v9, v113
	v_mov_b32_e32 v18, 0
	v_mov_b32_e32 v19, v113
	v_mov_b32_e32 v20, v113
	v_mov_b32_e32 v21, v113
	v_mov_b32_e32 v14, 0
	v_mov_b32_e32 v15, v113
	v_mov_b32_e32 v16, v113
	v_mov_b32_e32 v17, v113
	v_mov_b32_e32 v26, 0
	v_mov_b32_e32 v27, v113
	v_mov_b32_e32 v28, v113
	v_mov_b32_e32 v29, v113
	v_mov_b32_e32 v22, 0
	v_mov_b32_e32 v23, v113
	v_mov_b32_e32 v24, v113
	v_mov_b32_e32 v25, v113
	v_mov_b32_e32 v30, 0
	v_mov_b32_e32 v31, v113
	v_mov_b32_e32 v32, v113
	v_mov_b32_e32 v33, v113
	v_mov_b32_e32 v214, 0x11800
	ds_read_b32 v214, v214
	s_waitcnt lgkmcnt(0)

; #define MFMA16(a, b, c) __builtin_amdgcn_mfma_f32_16x16x32_bf16((a), (b), (c), 0, 0, 0)
; template <int MODE>
; __device__ __forceinline__ void attn_item(const Params& p, unsigned char* sm, int h, int tok0, int nrows, int kvt0, int ntiles, int nkeys, int qpos0, const int TIDX) {
;     ...
;         const unsigned char* Kb = sm + (t & 1) * 35840; const unsigned char* Vb = Kb + 17408;
;         f32x4 s[4];
; #pragma unroll
;         for (int kb = 0; kb < 4; ++kb) {
;             f32x4 acc = (f32x4){0.f, 0.f, 0.f, 0.f};
; #pragma unroll
;             for (int ks = 0; ks < KS; ++ks) {
;                 const bf16x8 A = *(const bf16x8*)(Kb + (16 * kb + r16) * 272 + (doff + 32 * ks + 8 * g) * 2);
;                 acc = MFMA16(A, Qf[ks], acc);
;             }
;             s[kb] = acc;
;         }
;         float mx = -1e30f;
;         if ((MODE == 1 || (64 * t + 63 - qpos0 <= -128)) && 64 * (t + 1) <= nkeys) {
;             const float bfar = MODE == 0 ? BIAS[0] : 0.f;
; #pragma unroll
;             for (int kb = 0; kb < 4; ++kb)
; #pragma unroll
;                 for (int j = 0; j < 4; ++j) { const float v = s[kb][j] * SC + bfar; s[kb][j] = v; mx = fmaxf(mx, v); }
.LBB0_97:
	s_bitcmp1_b32 s14, 0
	s_cselect_b32 s14, 0x8c00, 0
	s_add_i32 s24, s14, 0
	v_add3_u32 v62, s24, v107, v106
	v_add3_u32 v63, s24, v108, v106
	v_add3_u32 v64, s24, v109, v106
	v_add3_u32 v80, s24, v110, v106
	v_add3_u32 v212, s24, v74, v111
	ds_read_b128 v[120:123], v62
	ds_read_b128 v[124:127], v62 offset:64
	ds_read_b128 v[128:131], v63
	ds_read_b128 v[132:135], v63 offset:64
	ds_read_b128 v[136:139], v64
	ds_read_b128 v[140:143], v64 offset:64
	ds_read_b128 v[144:147], v80
	ds_read_b128 v[148:151], v80 offset:64
	v_add_u32_e32 v213, 0x4000, v212
	ds_read_b64 v[152:153], v213 offset:1024
	ds_read_b64 v[154:155], v213 offset:1056
	v_add_u32_e32 v213, 0x4000, v212
	ds_read_b64 v[156:157], v213 offset:1088
	ds_read_b64 v[158:159], v213 offset:1120
	v_add_u32_e32 v213, 0x4800, v212
	ds_read_b64 v[160:161], v213 offset:1280
	ds_read_b64 v[162:163], v213 offset:1312
	s_add_i32 s14, s19, s22
	s_sub_i32 s14, s14, 64
	s_cmpk_gt_i32 s14, 0xff41
	s_cselect_b64 s[14:15], -1, 0
	s_cmp_gt_i32 s22, s17
	s_cselect_b64 s[26:27], -1, 0
	s_or_b64 s[26:27], s[14:15], s[26:27]
	s_mov_b64 s[14:15], -1
	s_andn2_b64 vcc, exec, s[26:27]
	s_waitcnt lgkmcnt(12)
	v_mfma_f32_16x16x32_bf16 v[66:69], v[120:123], v[34:37], 0
	v_mfma_f32_16x16x32_bf16 v[66:69], v[124:127], v[38:41], v[66:69]
	v_add_u32_e32 v213, 0x4800, v212
	ds_read_b64 v[164:165], v213 offset:1344
	ds_read_b64 v[166:167], v213 offset:1376
	s_waitcnt lgkmcnt(12)
	v_mfma_f32_16x16x32_bf16 v[70:73], v[128:131], v[34:37], 0
	v_mfma_f32_16x16x32_bf16 v[70:73], v[132:135], v[38:41], v[70:73]
	v_add_u32_e32 v213, 0x5000, v212
	ds_read_b64 v[204:205], v213 offset:1536
	ds_read_b64 v[206:207], v213 offset:1568
	s_waitcnt lgkmcnt(12)
	v_mfma_f32_16x16x32_bf16 v[58:61], v[136:139], v[34:37], 0
	v_mfma_f32_16x16x32_bf16 v[58:61], v[140:143], v[38:41], v[58:61]
	v_add_u32_e32 v213, 0x5000, v212
	ds_read_b64 v[208:209], v213 offset:1600
	ds_read_b64 v[210:211], v213 offset:1632
	s_waitcnt lgkmcnt(12)
	v_mfma_f32_16x16x32_bf16 v[62:65], v[144:147], v[34:37], 0
	v_mfma_f32_16x16x32_bf16 v[62:65], v[148:151], v[38:41], v[62:65]
	s_nop 1
	v_mul_f32_e32 v66, 0x3e38aa3b, v66
	v_mul_f32_e32 v67, 0x3e38aa3b, v67
	s_cbranch_vccz .LBB0_99
	v_mov_b32_e32 v94, v214
	s_mov_b32 s26, 0x3e38aa3b
	s_mov_b32 s14, 0xf149f2ca
	v_pk_add_f32 v[84:85], v[66:67], v[94:95] op_sel_hi:[1,0]
	v_pk_fma_f32 v[86:87], v[68:69], s[26:27], v[94:95] op_sel_hi:[1,0,0]
	v_max3_f32 v90, v84, s14, v85
	v_pk_fma_f32 v[80:81], v[70:71], s[26:27], v[94:95] op_sel_hi:[1,0,0]
	v_max3_f32 v90, v90, v86, v87
	v_pk_fma_f32 v[82:83], v[72:73], s[26:27], v[94:95] op_sel_hi:[1,0,0]
	v_max3_f32 v90, v90, v80, v81
	v_pk_fma_f32 v[88:89], v[58:59], s[26:27], v[94:95] op_sel_hi:[1,0,0]
	v_max3_f32 v90, v90, v82, v83
	v_max3_f32 v92, v90, v88, v89
	v_pk_fma_f32 v[90:91], v[60:61], s[26:27], v[94:95] op_sel_hi:[1,0,0]
	s_mov_b64 s[14:15], 0
	v_max3_f32 v95, v92, v90, v91
	v_pk_fma_f32 v[92:93], v[62:63], s[26:27], v[94:95] op_sel_hi:[1,0,0]
	s_nop 0
	v_max3_f32 v115, v95, v92, v93
	v_pk_fma_f32 v[94:95], v[64:65], s[26:27], v[94:95] op_sel_hi:[1,0,0]
	s_nop 0
	v_max3_f32 v115, v115, v94, v95

; __device__ __forceinline__ void phase_post(const Params& p, unsigned char* sm, const int TIDX, const int BIDX) {
;     ...
;         if (G) {
;             float s = 0.f;
; #pragma unroll
;             for (int i = 0; i < 4; ++i) s += k4[i][0] * k4[i][0] + k4[i][1] * k4[i][1] + k4[i][2] * k4[i][2] + k4[i][3] * k4[i][3];
;             s += __shfl_xor(s, 1); s += __shfl_xor(s, 2); if (G == 128) s += __shfl_xor(s, 4);
;             const float rs = rsqrtf(s / (float)G + EPS);
; #pragma unroll
;             for (int i = 0; i < 4; ++i) { const f32x4 gg = *(const f32x4*)(gain + ((cseg * 16 + i * 4) & (G - 1))); k4[i] = k4[i] * rs * gg; }
;             if (ok) {
; #pragma unroll
;                 for (int i = 0; i < 4; ++i) *(f32x4*)(kdst + (size_t)r * 512 + cseg * 16 + i * 4) = k4[i];
;             }
.LBB0_229:
	v_cvt_f32_u32_e32 v2, s7
	s_add_i32 s7, s7, -1
	v_div_scale_f32 v3, s[12:13], v2, v2, v0
	v_rcp_f32_e32 v47, v3
	s_nop 0
	v_fma_f32 v49, -v3, v47, 1.0
	v_fmac_f32_e32 v47, v49, v47
	v_div_scale_f32 v49, vcc, v0, v2, v0
	v_mul_f32_e32 v51, v49, v47
	v_fma_f32 v52, -v3, v51, v49
	v_fmac_f32_e32 v51, v52, v47
	v_fma_f32 v3, -v3, v51, v49
	v_div_fmas_f32 v3, v3, v47, v51
	v_div_fixup_f32 v0, v3, v2, v0
	v_add_f32_e32 v0, 0x358637bd, v0
	v_cmp_gt_f32_e32 vcc, s97, v0
	v_mul_f32_e32 v2, 0x4b800000, v0
	s_nop 0
	v_cndmask_b32_e32 v0, v0, v2, vcc
	v_rsq_f32_e32 v0, v0
	s_nop 0
	v_mul_f32_e32 v2, 0x45800000, v0
	v_cndmask_b32_e32 v0, v0, v2, vcc
	v_and_b32_e32 v2, s7, v38
	v_lshlrev_b32_e32 v2, 2, v2
	v_and_b32_e32 v216, s7, v59
	v_lshlrev_b32_e32 v216, 2, v216
	v_and_b32_e32 v217, s7, v60
	v_lshlrev_b32_e32 v217, 2, v217
	v_and_b32_e32 v218, s7, v61
	v_lshlrev_b32_e32 v218, 2, v218
	global_load_dwordx4 v[52:55], v2, s[10:11]
	global_load_dwordx4 v[204:207], v216, s[10:11]
	global_load_dwordx4 v[208:211], v217, s[10:11]
	global_load_dwordx4 v[212:215], v218, s[10:11]
	v_pk_mul_f32 v[2:3], v[16:17], v[0:1] op_sel_hi:[1,0]
	v_pk_mul_f32 v[16:17], v[18:19], v[0:1] op_sel_hi:[1,0]
	s_waitcnt vmcnt(0)
	v_pk_mul_f32 v[18:19], v[54:55], v[16:17]
	v_pk_mul_f32 v[16:17], v[52:53], v[2:3]
	v_pk_mul_f32 v[2:3], v[24:25], v[0:1] op_sel_hi:[1,0]
	v_pk_mul_f32 v[24:25], v[26:27], v[0:1] op_sel_hi:[1,0]
	v_pk_mul_f32 v[26:27], v[206:207], v[24:25]
	v_pk_mul_f32 v[24:25], v[204:205], v[2:3]
	v_pk_mul_f32 v[2:3], v[28:29], v[0:1] op_sel_hi:[1,0]
	v_pk_mul_f32 v[28:29], v[30:31], v[0:1] op_sel_hi:[1,0]
	v_pk_mul_f32 v[30:31], v[210:211], v[28:29]
	v_pk_mul_f32 v[28:29], v[208:209], v[2:3]
	v_pk_mul_f32 v[2:3], v[32:33], v[0:1] op_sel_hi:[1,0]
	v_pk_mul_f32 v[32:33], v[34:35], v[0:1] op_sel_hi:[1,0]
	v_pk_mul_f32 v[34:35], v[214:215], v[32:33]
	v_pk_mul_f32 v[32:33], v[212:213], v[2:3]
	s_and_saveexec_b64 s[10:11], s[4:5]
	s_cbranch_execz .LBB0_202
	v_lshl_add_u64 v[2:3], s[8:9], 0, v[44:45]
	v_mov_b32_e32 v51, v1
	v_lshl_add_u64 v[2:3], v[2:3], 0, v[50:51]
	global_store_dwordx4 v[2:3], v[16:19], off
	global_store_dwordx4 v[2:3], v[24:27], off offset:16
	global_store_dwordx4 v[2:3], v[28:31], off offset:32
	global_store_dwordx4 v[2:3], v[32:35], off offset:48
	s_branch .LBB0_202
